# v52 + silu(z) for tokens 32-63 of the next super-chunk by waves 4-7 while waves 0-3 run step D (parked in v0-v3, stored in the next step A1): step A1 has no silu block after the first super-chunk
# baseline (speedup 1.0000x reference)
.LBB0_542:
	v_cmp_gt_i32_e64 s[22:23], s24, v89
	s_and_saveexec_b64 s[24:25], s[22:23]
	s_cbranch_execz .LBB0_544
	s_cmp_eq_u32 s29, 0
	s_cbranch_scc1 .Lsz_do
	s_and_b64 vcc, exec, s[36:37]
	s_cbranch_vccnz .Lsz_do
	s_and_b64 vcc, exec, s[26:27]
	s_cbranch_vccnz .LBB0_544
	ds_write_b128 v146, v[0:3]
	s_branch .LBB0_544

.Lsz_skip2:
	s_waitcnt vmcnt(1)
	s_waitcnt lgkmcnt(0)
	s_barrier
	s_and_b64 vcc, exec, s[56:57]
	s_cbranch_vccnz .Lsz_skip3
	ds_read_b128 v[20:23], v143
	ds_read_b128 v[24:27], v145
	ds_read_b128 v[28:31], v225
	s_waitcnt lgkmcnt(1)
	v_sub_f16_e32 v8, v24, v20
	v_sub_f16_sdwa v9, v24, v20 dst_sel:DWORD dst_unused:UNUSED_PAD src0_sel:WORD_1 src1_sel:WORD_1
	v_sub_f16_e32 v11, v25, v21
	v_sub_f16_sdwa v24, v25, v21 dst_sel:DWORD dst_unused:UNUSED_PAD src0_sel:WORD_1 src1_sel:WORD_1
	v_sub_f16_e32 v32, v27, v23
	v_sub_f16_sdwa v27, v27, v23 dst_sel:DWORD dst_unused:UNUSED_PAD src0_sel:WORD_1 src1_sel:WORD_1
	v_sub_f16_e32 v25, v26, v22
	v_sub_f16_sdwa v26, v26, v22 dst_sel:DWORD dst_unused:UNUSED_PAD src0_sel:WORD_1 src1_sel:WORD_1
	v_pack_b32_f16 v27, v32, v27
	v_pack_b32_f16 v11, v11, v24
	s_waitcnt lgkmcnt(0)
	v_pk_fma_f16 v31, v31, v27, v23
	v_pack_b32_f16 v23, v25, v26
	v_pk_fma_f16 v11, v29, v11, v21
	v_pk_fma_f16 v27, v30, v23, v22
	v_fma_mix_f32 v23, v11, s87, 0 op_sel_hi:[1,0,0]
	v_cvt_f32_f16_e32 v22, v11
	v_exp_f32_e32 v24, v23
	v_fma_mix_f32 v23, v11, s87, 0 op_sel:[1,0,0] op_sel_hi:[1,0,0]
	v_pack_b32_f16 v8, v8, v9
	v_exp_f32_e32 v25, v23
	v_cvt_f32_f16_sdwa v23, v11 dst_sel:DWORD dst_unused:UNUSED_PAD src0_sel:WORD_1
	v_add_f32_e32 v11, 1.0, v24
	v_rcp_f32_e32 v24, v11
	v_add_f32_e32 v11, 1.0, v25
	v_rcp_f32_e32 v25, v11
	v_fma_mix_f32 v11, v27, s87, 0 op_sel_hi:[1,0,0]
	v_pk_fma_f16 v9, v28, v8, v20
	v_exp_f32_e32 v11, v11
	v_fma_mix_f32 v28, v27, s87, 0 op_sel:[1,0,0] op_sel_hi:[1,0,0]
	v_fma_mix_f32 v20, v9, s87, 0 op_sel_hi:[1,0,0]
	v_exp_f32_e32 v29, v28
	v_add_f32_e32 v11, 1.0, v11
	v_rcp_f32_e32 v28, v11
	v_fma_mix_f32 v21, v9, s87, 0 op_sel:[1,0,0] op_sel_hi:[1,0,0]
	v_add_f32_e32 v11, 1.0, v29
	v_rcp_f32_e32 v29, v11
	v_fma_mix_f32 v11, v31, s87, 0 op_sel_hi:[1,0,0]
	v_fma_mix_f32 v32, v31, s87, 0 op_sel:[1,0,0] op_sel_hi:[1,0,0]
	v_exp_f32_e32 v11, v11
	v_exp_f32_e32 v20, v20
	v_exp_f32_e32 v21, v21
	v_exp_f32_e32 v33, v32
	v_add_f32_e32 v11, 1.0, v11
	v_add_f32_e32 v20, 1.0, v20
	v_add_f32_e32 v21, 1.0, v21
	v_rcp_f32_e32 v32, v11
	v_add_f32_e32 v11, 1.0, v33
	v_cvt_f32_f16_e32 v8, v9
	v_cvt_f32_f16_sdwa v9, v9 dst_sel:DWORD dst_unused:UNUSED_PAD src0_sel:WORD_1
	v_rcp_f32_e32 v20, v20
	v_rcp_f32_e32 v21, v21
	v_cvt_f32_f16_e32 v26, v27
	v_cvt_f32_f16_sdwa v27, v27 dst_sel:DWORD dst_unused:UNUSED_PAD src0_sel:WORD_1
	v_cvt_f32_f16_e32 v30, v31
	v_cvt_f32_f16_sdwa v31, v31 dst_sel:DWORD dst_unused:UNUSED_PAD src0_sel:WORD_1
	v_rcp_f32_e32 v33, v11
	v_pk_fma_f32 v[8:9], v[8:9], v[20:21], 0 op_sel_hi:[1,1,0]
	v_pk_fma_f32 v[20:21], v[22:23], v[24:25], 0 op_sel_hi:[1,1,0]
	v_pk_fma_f32 v[24:25], v[26:27], v[28:29], 0 op_sel_hi:[1,1,0]
	v_pk_fma_f32 v[22:23], v[30:31], v[32:33], 0 op_sel_hi:[1,1,0]
	v_cvt_pk_f16_f32 v1, v20, v21
	v_cvt_pk_f16_f32 v3, v22, v23
	v_cvt_pk_f16_f32 v2, v24, v25
	v_cvt_pk_f16_f32 v0, v8, v9
.Lsz_skip3:
	s_branch .Lds_after
.LBB0_592:
	v_readlane_b32 s96, v255, 33
	s_cmpk_gt_u32 s96, 0xff
	s_cbranch_scc1 .LBB0_594
	v_readlane_b32 s4, v255, 0
	v_readlane_b32 s5, v255, 1
	v_readlane_b32 s6, v255, 2
	v_readlane_b32 s7, v255, 3
	v_readlane_b32 s8, v255, 4
	v_readlane_b32 s9, v255, 5
	s_mov_b32 s3, 0x82b1000
	s_and_b64 s[0:1], s[36:37], exec
	v_readlane_b32 s10, v255, 6
	v_readlane_b32 s11, v255, 7
	s_mov_b64 s[4:5], s[8:9]
	s_cselect_b32 s0, s3, 0x8080000
	s_mov_b64 s[6:7], s[10:11]
	s_add_u32 s0, s6, s0
	s_addc_u32 s1, s7, 0
	s_waitcnt lgkmcnt(0)
	v_lshl_add_u64 v[8:9], s[0:1], 0, v[46:47]
	v_lshlrev_b32_e32 v10, 2, v90
	v_mov_b32_e32 v11, 0
	v_lshl_add_u64 v[8:9], v[8:9], 0, v[10:11]
	global_store_dwordx4 v[8:9], v[0:3], off
	global_store_dwordx4 v[8:9], v[4:7], off offset:64
	global_store_dwordx4 v[8:9], v[12:15], off offset:128
	global_store_dwordx4 v[8:9], v[16:19], off offset:192
